# grid barrier leader path: no trailing waits after the release atomics
# baseline (speedup 1.0000x reference)
.LBB0_560:
	s_or_b64 exec, exec, s[8:9]
	s_mov_b64 s[8:9], exec
	v_mbcnt_lo_u32_b32 v0, s8, 0
	v_mbcnt_hi_u32_b32 v0, s9, v0
	v_cmp_eq_u32_e32 vcc, 0, v0
	s_nop 0
	s_and_saveexec_b64 s[10:11], vcc
	s_cbranch_execz .LBB0_562
	s_bcnt1_i32_b64 s0, s[8:9]
	v_mov_b32_e32 v0, 0x2000
	v_mov_b32_e32 v1, s0
	global_atomic_add v0, v1, s[6:7] offset:1024
.LBB0_562:
	s_or_b64 exec, exec, s[10:11]
	s_nop 0
